# DIFF fast path: removed in-loop vmcnt(0) that drained next-tile LDS-DMA before reading current-stage positions
# speedup vs baseline: 1.0421x; 1.0018x over previous
; #define MFMA(a, b, c) __builtin_amdgcn_mfma_f32_32x32x16_bf16((a), (b), (c), 0, 0, 0)
; DI int tid_pinned() { int t = threadIdx.x; asm volatile("" : "+v"(t)); return t; }
; DI f32x16 zero16() { f32x16 z; for (int r = 0; r < 16; ++r) z[r] = 0.f; return z; }
; #define DIFF_MASK(sv, sub_) do { if (needmask) { _Pragma("unroll") for (int r = 0; r < 16; ++r) { const int kl_ = (sub_) * 32 + ((r < 8) ? (8 * g2 + r) : (16 + 8 * g2 + (r - 8))); \
;           if ((pki[kl_] >> 6) > (((int)qposf) >> 6)) sv[r] = -__builtin_inff(); } } } while (0)
; template <bool DIFF>
; DI void attn_phase(const AttnArgs& a, char* lds) {
;     ...
;       if (DIFF && uft != 0 && !skip) {
;         const int* pki = (const int*)(sb + KBYTES + VBYTES);
;         const float* pkf = (const float*)(sb + KBYTES + VBYTES + 256);
;         const int l2 = tid_pinned() & 63, l31b = l2 & 31, g2 = l2 >> 5;
;         const int prow = (((l31b >> 4) & 1) << 4) | (((l31b >> 2) & 1) << 3) | (((l31b >> 3) & 1) << 2) | (l31b & 3);
;         const int kx = g2 ^ ((prow >> 1) & 7);
;         const int koffb = comp * 16384 + prow * 128;
;         const int vx = g2 ^ ((l31b >> 1) & 7);
;         const int voffb = KBYTES + l31b * 128;
;     ...
;         bf16x8 kf[NDS];
; #pragma unroll
;         for (int ds = 0; ds < NDS; ++ds) kf[ds] = *(const bf16x8*)(sb + koffb + (ds >> 2) * 8192 + ((((ds & 3) * 2) ^ kx) << 4));
;         f32x16 s0, s1;
;         s0 = MFMA(kf[0], qf[0], zero16());
; #pragma unroll
;         for (int ds = 1; ds < NDS; ++ds) s0 = MFMA(kf[ds], qf[ds], s0);
; #pragma unroll
;         for (int ds = 0; ds < NDS; ++ds) kf[ds] = *(const bf16x8*)(sb + koffb + 4096 + (ds >> 2) * 8192 + ((((ds & 3) * 2) ^ kx) << 4));
;         __builtin_amdgcn_sched_barrier(0);
;         {
;           s1 = MFMA(kf[0], qf[0], zero16());
; #pragma unroll
;           for (int ds = 1; ds < NDS; ++ds) s1 = MFMA(kf[ds], qf[ds], s1);
;           DIFF_ALIBI(s0, 0);
;           DIFF_MASK(s0, 0);
.LBB0_602:
	s_nop 0
	v_subrev_u32_e32 v0, s8, v219
	v_sub_u32_e32 v2, s5, v217
	v_max3_i32 v0, v0, v2, 0
	v_cvt_f32_u32_e32 v0, v0
	s_bitcmp1_b32 s1, 0
	s_cselect_b32 s84, 0x10200, 0
	s_cmp_gt_i32 s0, s77
	v_mul_f32_e32 v0, v223, v0
	s_cselect_b64 s[0:1], -1, 0
	v_cmp_gt_f32_e32 vcc, v0, v218
	v_mov_b32_e32 v0, v222
	s_or_b64 s[68:69], s[0:1], vcc
	s_nop 0
	v_readfirstlane_b32 s0, v0
	s_cmp_eq_u32 s0, 0
	s_cselect_b64 s[8:9], -1, 0
	s_or_b64 s[8:9], s[8:9], s[68:69]
	s_and_b64 vcc, exec, s[8:9]
	v_cmp_gt_i32_e64 s[8:9], s4, v220
	s_nop 1
	v_cndmask_b32_e64 v0, 0, 1, s[8:9]
	v_cmp_ne_u32_e64 s[8:9], 1, v0
	s_cbranch_vccnz .LBB0_608
	v_mov_b32_e32 v2, v208
	s_add_i32 s1, s35, s84
	v_lshlrev_b32_e32 v3, 1, v2
	v_and_b32_e32 v4, 8, v3
	v_lshrrev_b32_e32 v3, 1, v2
	v_and_b32_e32 v5, 4, v3
	v_and_b32_e32 v6, 19, v2
	v_or3_b32 v4, v4, v6, v5
	v_bfe_u32 v0, v2, 5, 1
	v_lshrrev_b32_e32 v5, 1, v4
	v_bitop3_b32 v5, v5, v0, 7 bitop3:0x6c
	v_lshl_add_u32 v144, v4, 7, s1
	v_lshlrev_b32_e32 v145, 4, v5
	v_add_u32_e32 v146, v144, v145
	ds_read_b128 v[4:7], v146
	v_xad_u32 v147, v145, 32, v144
	v_xad_u32 v148, v145, 64, v144
	s_waitcnt lgkmcnt(0)
	v_mfma_f32_32x32x16_bf16 v[160:175], v[4:7], v[176:179], 0
	ds_read_b128 v[4:7], v147
	v_xad_u32 v144, v145, s74, v144
	ds_read_b128 v[8:11], v146 offset:4096
	ds_read_b128 v[12:15], v147 offset:4096
	ds_read_b128 v[228:231], v148 offset:4096
	v_lshlrev_b32_e32 v252, 5, v0
	v_add_u32_e32 v227, s84, v252
	s_waitcnt lgkmcnt(0)
	v_mfma_f32_32x32x16_bf16 v[160:175], v[4:7], v[180:183], v[160:175]
	ds_read_b128 v[4:7], v148
	s_add_i32 s1, s84, 0x10000
	s_waitcnt lgkmcnt(0)
	v_mfma_f32_32x32x16_bf16 v[160:175], v[4:7], v[184:187], v[160:175]
	ds_read_b128 v[4:7], v144
	ds_read_b128 v[232:235], v144 offset:4096
	s_waitcnt lgkmcnt(0)
	v_mfma_f32_32x32x16_bf16 v[160:175], v[4:7], v[188:191], v[160:175]
	ds_read_b128 v[4:7], v146 offset:8192
	ds_read_b128 v[236:239], v146 offset:12288
	s_waitcnt lgkmcnt(0)
	v_mfma_f32_32x32x16_bf16 v[160:175], v[4:7], v[192:195], v[160:175]
	ds_read_b128 v[4:7], v147 offset:8192
	ds_read_b128 v[240:243], v147 offset:12288
	s_waitcnt lgkmcnt(0)
	v_mfma_f32_32x32x16_bf16 v[160:175], v[4:7], v[196:199], v[160:175]
	ds_read_b128 v[4:7], v148 offset:8192
	ds_read_b128 v[244:247], v148 offset:12288
	ds_read_b128 v[248:251], v144 offset:12288
	s_waitcnt lgkmcnt(0)
	v_mfma_f32_32x32x16_bf16 v[160:175], v[4:7], v[200:203], v[160:175]
	ds_read_b128 v[4:7], v144 offset:8192
	s_waitcnt lgkmcnt(0)
	v_mfma_f32_32x32x16_bf16 v[160:175], v[4:7], v[204:207], v[160:175]
	v_mfma_f32_32x32x16_bf16 v[144:159], v[8:11], v[176:179], 0
	v_add_u32_e32 v253, 0x10100, v227
	ds_read_b128 v[4:7], v253
	ds_read_b128 v[8:11], v253 offset:16
	s_and_b64 vcc, exec, s[8:9]
	s_waitcnt lgkmcnt(1)
	v_sub_f32_e32 v4, v221, v4
	v_sub_f32_e32 v5, v221, v5
	v_mfma_f32_32x32x16_bf16 v[144:159], v[12:15], v[180:183], v[144:159]
	v_sub_f32_e32 v6, v221, v6
	v_sub_f32_e32 v7, v221, v7
	s_waitcnt lgkmcnt(0)
	v_sub_f32_e32 v12, v221, v8
	v_sub_f32_e32 v13, v221, v9
	v_sub_f32_e32 v14, v221, v10
	v_sub_f32_e32 v15, v221, v11
	v_mfma_f32_32x32x16_bf16 v[144:159], v[228:231], v[184:187], v[144:159]
	v_fma_f32 v11, -v223, |v4|, v160
	v_fma_f32 v9, -v223, |v5|, v161
	v_fma_f32 v10, -v223, |v6|, v162
	v_fma_f32 v8, -v223, |v7|, v163
	v_fma_f32 v7, -v223, |v12|, v164
	v_fma_f32 v6, -v223, |v13|, v165
	v_fma_f32 v5, -v223, |v14|, v166
	v_mfma_f32_32x32x16_bf16 v[144:159], v[232:235], v[188:191], v[144:159]
	v_fma_f32 v4, -v223, |v15|, v167
	ds_read_b128 v[12:15], v253 offset:64
	ds_read_b128 v[160:163], v253 offset:80
	s_waitcnt lgkmcnt(1)
	v_sub_f32_e32 v12, v221, v12
	v_mfma_f32_32x32x16_bf16 v[144:159], v[236:239], v[192:195], v[144:159]
	v_sub_f32_e32 v13, v221, v13
	v_sub_f32_e32 v14, v221, v14
	v_sub_f32_e32 v15, v221, v15
	s_waitcnt lgkmcnt(0)
	v_sub_f32_e32 v165, v221, v160
	v_sub_f32_e32 v166, v221, v161
	v_sub_f32_e32 v167, v221, v162
	v_sub_f32_e32 v163, v221, v163
	v_mfma_f32_32x32x16_bf16 v[144:159], v[240:243], v[196:199], v[144:159]
	s_nop 0
	v_fma_f32 v164, -v223, |v12|, v168
	v_fma_f32 v162, -v223, |v13|, v169
	v_fma_f32 v160, -v223, |v14|, v170
	v_fma_f32 v161, -v223, |v15|, v171
	v_fma_f32 v15, -v223, |v165|, v172
	v_mfma_f32_32x32x16_bf16 v[144:159], v[244:247], v[200:203], v[144:159]
	v_fma_f32 v14, -v223, |v166|, v173
	v_fma_f32 v13, -v223, |v167|, v174
	v_fma_f32 v12, -v223, |v163|, v175
	v_add_u32_e32 v163, s1, v252
	v_mfma_f32_32x32x16_bf16 v[144:159], v[248:251], v[204:207], v[144:159]
	s_cbranch_vccnz .LBB0_605
	ds_read_b128 v[166:169], v163
	v_add_u32_e32 v165, 0x10050, v227
	ds_read_b128 v[170:173], v165
	s_waitcnt lgkmcnt(1)
	v_ashrrev_i32_e32 v165, 6, v166
	v_ashrrev_i32_e32 v166, 6, v167
	v_cmp_le_i32_e32 vcc, v165, v224
	v_ashrrev_i32_e32 v165, 6, v168
	s_nop 0
	v_cndmask_b32_e32 v11, v216, v11, vcc
	v_cmp_le_i32_e32 vcc, v166, v224
	v_add_u32_e32 v166, 0x10010, v227
	s_nop 0
	v_cndmask_b32_e32 v9, v216, v9, vcc
	v_cmp_le_i32_e32 vcc, v165, v224
	v_ashrrev_i32_e32 v165, 6, v169
	ds_read_b128 v[166:169], v166
	v_cndmask_b32_e32 v10, v216, v10, vcc
	v_cmp_le_i32_e32 vcc, v165, v224
	v_add_u32_e32 v165, 0x10040, v227
	ds_read_b128 v[228:231], v165
	s_waitcnt lgkmcnt(1)
	v_ashrrev_i32_e32 v165, 6, v166
	v_cndmask_b32_e32 v8, v216, v8, vcc
	v_cmp_le_i32_e32 vcc, v165, v224
	v_ashrrev_i32_e32 v165, 6, v167
	s_nop 0
	v_cndmask_b32_e32 v7, v216, v7, vcc
	v_cmp_le_i32_e32 vcc, v165, v224
	v_ashrrev_i32_e32 v165, 6, v168
	s_nop 0
	v_cndmask_b32_e32 v6, v216, v6, vcc
	v_cmp_le_i32_e32 vcc, v165, v224
	v_ashrrev_i32_e32 v165, 6, v169
	s_nop 0
	v_cndmask_b32_e32 v5, v216, v5, vcc
	v_cmp_le_i32_e32 vcc, v165, v224
	s_waitcnt lgkmcnt(0)
	v_ashrrev_i32_e32 v165, 6, v228
	v_cndmask_b32_e32 v4, v216, v4, vcc
	v_cmp_le_i32_e32 vcc, v165, v224
	v_ashrrev_i32_e32 v165, 6, v229
	s_nop 0
	v_cndmask_b32_e32 v164, v216, v164, vcc
	v_cmp_le_i32_e32 vcc, v165, v224
	v_ashrrev_i32_e32 v165, 6, v230
	s_nop 0
	v_cndmask_b32_e32 v162, v216, v162, vcc
	v_cmp_le_i32_e32 vcc, v165, v224
	v_ashrrev_i32_e32 v165, 6, v231
	s_nop 0
	v_cndmask_b32_e32 v160, v216, v160, vcc
	v_cmp_le_i32_e32 vcc, v165, v224
	v_ashrrev_i32_e32 v165, 6, v170
	s_nop 0
	v_cndmask_b32_e32 v161, v216, v161, vcc
	v_cmp_le_i32_e32 vcc, v165, v224
	v_ashrrev_i32_e32 v165, 6, v171
	s_nop 0
	v_cndmask_b32_e32 v15, v216, v15, vcc
	v_cmp_le_i32_e32 vcc, v165, v224
	v_ashrrev_i32_e32 v165, 6, v172
	s_nop 0
	v_cndmask_b32_e32 v14, v216, v14, vcc
	v_cmp_le_i32_e32 vcc, v165, v224
	v_ashrrev_i32_e32 v165, 6, v173
	s_nop 0
	v_cndmask_b32_e32 v13, v216, v13, vcc
	v_cmp_le_i32_e32 vcc, v165, v224
	s_nop 1
	v_cndmask_b32_e32 v12, v216, v12, vcc
